# P6 epilogue: bf16 stores lane-permuted (ds_bpermute) so 4 consecutive lanes cover one 64B row piece
# speedup vs baseline: 1.0094x; 1.0094x over previous
.LBB0_731:
	ds_read_b128 v[148:151], v156
	ds_read_b128 v[160:163], v156 offset:1024
	ds_read_b128 v[164:167], v156 offset:2048
	ds_read_b128 v[168:171], v156 offset:3072
	ds_read_b128 v[176:179], v157
	ds_read_b128 v[180:183], v157 offset:1024
	ds_read_b128 v[184:187], v157 offset:2048
	ds_read_b128 v[188:191], v157 offset:3072
	s_add_u32 s22, s0, 0xfff00080
	s_addc_u32 s23, s1, -1
	s_cmp_eq_u32 s61, 60
	s_cselect_b32 s25, s5, s23
	s_cselect_b32 s24, s57, s22
	s_cselect_b32 s23, s21, s60
	s_cselect_b32 s22, s58, s59
	v_lshl_add_u64 v[152:153], s[0:1], 0, v[140:141]
	s_add_i32 m0, s34, 0xc000
	ds_read_b128 v[192:195], v158
	ds_read_b128 v[196:199], v158 offset:1024
	ds_read_b128 v[200:203], v158 offset:2048
	ds_read_b128 v[204:207], v158 offset:3072
	ds_read_b128 v[208:211], v158 offset:4096
	ds_read_b128 v[212:215], v158 offset:5120
	ds_read_b128 v[216:219], v158 offset:6144
	ds_read_b128 v[220:223], v158 offset:7168
	global_load_lds_dwordx4 v[152:153], off
	v_lshl_add_u64 v[152:153], s[0:1], 0, v[142:143]
	s_add_i32 m0, s34, 0xe000
	s_nop 0
	global_load_lds_dwordx4 v[152:153], off
	s_waitcnt vmcnt(8)
	s_waitcnt lgkmcnt(0)
	s_barrier
	s_setprio 1
	s_waitcnt lgkmcnt(0)
	v_mfma_f32_16x16x32_bf16 v[126:129], v[148:151], v[192:195], v[126:129]
	v_mfma_f32_16x16x32_bf16 v[122:125], v[164:167], v[192:195], v[122:125]
	v_mfma_f32_16x16x32_bf16 v[110:113], v[148:151], v[200:203], v[110:113]
	v_mfma_f32_16x16x32_bf16 v[106:109], v[164:167], v[200:203], v[106:109]
	v_mfma_f32_16x16x32_bf16 v[94:97], v[148:151], v[208:211], v[94:97]
	v_mfma_f32_16x16x32_bf16 v[90:93], v[164:167], v[208:211], v[90:93]
	v_mfma_f32_16x16x32_bf16 v[78:81], v[148:151], v[216:219], v[78:81]
	v_mfma_f32_16x16x32_bf16 v[74:77], v[164:167], v[216:219], v[74:77]
	v_mfma_f32_16x16x32_bf16 v[126:129], v[160:163], v[196:199], v[126:129]
	v_mfma_f32_16x16x32_bf16 v[122:125], v[168:171], v[196:199], v[122:125]
	v_mfma_f32_16x16x32_bf16 v[110:113], v[160:163], v[204:207], v[110:113]
	v_mfma_f32_16x16x32_bf16 v[106:109], v[168:171], v[204:207], v[106:109]
	v_mfma_f32_16x16x32_bf16 v[94:97], v[160:163], v[212:215], v[94:97]
	v_mfma_f32_16x16x32_bf16 v[90:93], v[168:171], v[212:215], v[90:93]
	v_mfma_f32_16x16x32_bf16 v[78:81], v[160:163], v[220:223], v[78:81]
	v_mfma_f32_16x16x32_bf16 v[74:77], v[168:171], v[220:223], v[74:77]
	s_setprio 0
	s_setprio 1
	v_mfma_f32_16x16x32_bf16 v[118:121], v[176:179], v[192:195], v[118:121]
	v_mfma_f32_16x16x32_bf16 v[114:117], v[184:187], v[192:195], v[114:117]
	v_mfma_f32_16x16x32_bf16 v[102:105], v[176:179], v[200:203], v[102:105]
	v_mfma_f32_16x16x32_bf16 v[98:101], v[184:187], v[200:203], v[98:101]
	v_mfma_f32_16x16x32_bf16 v[86:89], v[176:179], v[208:211], v[86:89]
	v_mfma_f32_16x16x32_bf16 v[82:85], v[184:187], v[208:211], v[82:85]
	v_mfma_f32_16x16x32_bf16 v[70:73], v[176:179], v[216:219], v[70:73]
	v_mfma_f32_16x16x32_bf16 v[66:69], v[184:187], v[216:219], v[66:69]
	v_mfma_f32_16x16x32_bf16 v[118:121], v[180:183], v[196:199], v[118:121]
	v_mfma_f32_16x16x32_bf16 v[114:117], v[188:191], v[196:199], v[114:117]
	v_mfma_f32_16x16x32_bf16 v[102:105], v[180:183], v[204:207], v[102:105]
	v_mfma_f32_16x16x32_bf16 v[98:101], v[188:191], v[204:207], v[98:101]
	v_mfma_f32_16x16x32_bf16 v[86:89], v[180:183], v[212:215], v[86:89]
	v_mfma_f32_16x16x32_bf16 v[82:85], v[188:191], v[212:215], v[82:85]
	v_mfma_f32_16x16x32_bf16 v[70:73], v[180:183], v[220:223], v[70:73]
	v_mfma_f32_16x16x32_bf16 v[66:69], v[188:191], v[220:223], v[66:69]
	s_setprio 0
	s_barrier
	s_add_i32 s62, s44, s31
	v_lshl_add_u64 v[152:153], s[22:23], 0, v[136:137]
	s_mov_b32 m0, s62
	ds_read_b128 v[192:195], v158 offset:16384
	ds_read_b128 v[196:199], v158 offset:17408
	ds_read_b128 v[200:203], v158 offset:18432
	ds_read_b128 v[204:207], v158 offset:19456
	ds_read_b128 v[208:211], v158 offset:20480
	ds_read_b128 v[212:215], v158 offset:21504
	ds_read_b128 v[216:219], v158 offset:22528
	ds_read_b128 v[220:223], v158 offset:23552
	global_load_lds_dwordx4 v[152:153], off
	s_add_i32 m0, s62, 0x2000
	s_add_u32 s62, s22, 0x100000
	v_lshl_add_u64 v[172:173], s[22:23], 0, v[130:131]
	s_addc_u32 s63, s23, 0
	s_add_i32 s64, s45, s31
	global_load_lds_dwordx4 v[172:173], off
	v_lshl_add_u64 v[224:225], s[62:63], 0, v[136:137]
	s_mov_b32 m0, s64
	v_lshl_add_u64 v[226:227], s[24:25], 0, v[132:133]
	global_load_lds_dwordx4 v[224:225], off
	v_lshl_add_u64 v[224:225], s[62:63], 0, v[130:131]
	s_add_i32 m0, s64, 0x2000
	s_nop 0
	global_load_lds_dwordx4 v[224:225], off
	v_lshl_add_u64 v[224:225], s[24:25], 0, v[138:139]
	s_mov_b32 m0, s34
	s_nop 0
	global_load_lds_dwordx4 v[224:225], off
	s_mov_b32 m0, s35
	s_nop 0
	global_load_lds_dwordx4 v[226:227], off
	s_waitcnt vmcnt(8)
	s_waitcnt lgkmcnt(0)
	s_barrier
	s_setprio 1
	s_waitcnt lgkmcnt(0)
	v_mfma_f32_16x16x32_bf16 v[62:65], v[148:151], v[192:195], v[62:65]
	v_mfma_f32_16x16x32_bf16 v[58:61], v[164:167], v[192:195], v[58:61]
	v_mfma_f32_16x16x32_bf16 v[46:49], v[148:151], v[200:203], v[46:49]
	v_mfma_f32_16x16x32_bf16 v[42:45], v[164:167], v[200:203], v[42:45]
	v_mfma_f32_16x16x32_bf16 v[30:33], v[148:151], v[208:211], v[30:33]
	v_mfma_f32_16x16x32_bf16 v[26:29], v[164:167], v[208:211], v[26:29]
	v_mfma_f32_16x16x32_bf16 v[14:17], v[148:151], v[216:219], v[14:17]
	v_mfma_f32_16x16x32_bf16 v[10:13], v[164:167], v[216:219], v[10:13]
	v_mfma_f32_16x16x32_bf16 v[62:65], v[160:163], v[196:199], v[62:65]
	v_mfma_f32_16x16x32_bf16 v[58:61], v[168:171], v[196:199], v[58:61]
	v_mfma_f32_16x16x32_bf16 v[46:49], v[160:163], v[204:207], v[46:49]
	v_mfma_f32_16x16x32_bf16 v[42:45], v[168:171], v[204:207], v[42:45]
	v_mfma_f32_16x16x32_bf16 v[30:33], v[160:163], v[212:215], v[30:33]
	v_mfma_f32_16x16x32_bf16 v[26:29], v[168:171], v[212:215], v[26:29]
	v_mfma_f32_16x16x32_bf16 v[14:17], v[160:163], v[220:223], v[14:17]
	v_mfma_f32_16x16x32_bf16 v[10:13], v[168:171], v[220:223], v[10:13]
	s_setprio 0
	s_setprio 1
	v_mfma_f32_16x16x32_bf16 v[54:57], v[176:179], v[192:195], v[54:57]
	v_mfma_f32_16x16x32_bf16 v[50:53], v[184:187], v[192:195], v[50:53]
	v_mfma_f32_16x16x32_bf16 v[38:41], v[176:179], v[200:203], v[38:41]
	v_mfma_f32_16x16x32_bf16 v[34:37], v[184:187], v[200:203], v[34:37]
	v_mfma_f32_16x16x32_bf16 v[22:25], v[176:179], v[208:211], v[22:25]
	v_mfma_f32_16x16x32_bf16 v[18:21], v[184:187], v[208:211], v[18:21]
	v_mfma_f32_16x16x32_bf16 v[6:9], v[176:179], v[216:219], v[6:9]
	v_mfma_f32_16x16x32_bf16 v[2:5], v[184:187], v[216:219], v[2:5]
	v_mfma_f32_16x16x32_bf16 v[54:57], v[180:183], v[196:199], v[54:57]
	v_mfma_f32_16x16x32_bf16 v[50:53], v[188:191], v[196:199], v[50:53]
	v_mfma_f32_16x16x32_bf16 v[38:41], v[180:183], v[204:207], v[38:41]
	v_mfma_f32_16x16x32_bf16 v[34:37], v[188:191], v[204:207], v[34:37]
	v_mfma_f32_16x16x32_bf16 v[22:25], v[180:183], v[212:215], v[22:25]
	v_mfma_f32_16x16x32_bf16 v[18:21], v[188:191], v[212:215], v[18:21]
	v_mfma_f32_16x16x32_bf16 v[6:9], v[180:183], v[220:223], v[6:9]
	v_mfma_f32_16x16x32_bf16 v[2:5], v[188:191], v[220:223], v[2:5]
	s_setprio 0
	s_barrier
	s_add_i32 s62, 0, 0x18000
	v_add_u32_e32 v159, s62, v135
	s_add_i32 s63, 0, 0x1c000
	ds_read_b128 v[148:151], v159
	ds_read_b128 v[160:163], v159 offset:1024
	ds_read_b128 v[164:167], v159 offset:2048
	ds_read_b128 v[168:171], v159 offset:3072
	v_add_u32_e32 v159, s63, v135
	ds_read_b128 v[176:179], v159
	ds_read_b128 v[180:183], v159 offset:1024
	ds_read_b128 v[184:187], v159 offset:2048
	ds_read_b128 v[188:191], v159 offset:3072
	s_add_u32 s24, s24, 0x100000
	s_addc_u32 s25, s25, 0
	s_mov_b32 m0, s36
	v_lshl_add_u64 v[228:229], s[24:25], 0, v[138:139]
	ds_read_b128 v[192:195], v158 offset:32768
	ds_read_b128 v[196:199], v158 offset:33792
	ds_read_b128 v[200:203], v158 offset:34816
	ds_read_b128 v[204:207], v158 offset:35840
	ds_read_b128 v[208:211], v158 offset:36864
	ds_read_b128 v[212:215], v158 offset:37888
	ds_read_b128 v[216:219], v158 offset:38912
	ds_read_b128 v[220:223], v158 offset:39936
	global_load_lds_dwordx4 v[228:229], off
	v_lshl_add_u64 v[228:229], s[24:25], 0, v[132:133]
	s_mov_b32 m0, s37
	s_nop 0
	global_load_lds_dwordx4 v[228:229], off
	s_waitcnt vmcnt(8)
	s_waitcnt lgkmcnt(0)
	s_barrier
	s_setprio 1
	s_waitcnt lgkmcnt(0)
	v_mfma_f32_16x16x32_bf16 v[126:129], v[148:151], v[192:195], v[126:129]
	v_mfma_f32_16x16x32_bf16 v[122:125], v[164:167], v[192:195], v[122:125]
	v_mfma_f32_16x16x32_bf16 v[110:113], v[148:151], v[200:203], v[110:113]
	v_mfma_f32_16x16x32_bf16 v[106:109], v[164:167], v[200:203], v[106:109]
	v_mfma_f32_16x16x32_bf16 v[94:97], v[148:151], v[208:211], v[94:97]
	v_mfma_f32_16x16x32_bf16 v[90:93], v[164:167], v[208:211], v[90:93]
	v_mfma_f32_16x16x32_bf16 v[78:81], v[148:151], v[216:219], v[78:81]
	v_mfma_f32_16x16x32_bf16 v[74:77], v[164:167], v[216:219], v[74:77]
	v_mfma_f32_16x16x32_bf16 v[126:129], v[160:163], v[196:199], v[126:129]
	v_mfma_f32_16x16x32_bf16 v[122:125], v[168:171], v[196:199], v[122:125]
	v_mfma_f32_16x16x32_bf16 v[110:113], v[160:163], v[204:207], v[110:113]
	v_mfma_f32_16x16x32_bf16 v[106:109], v[168:171], v[204:207], v[106:109]
	v_mfma_f32_16x16x32_bf16 v[94:97], v[160:163], v[212:215], v[94:97]
	v_mfma_f32_16x16x32_bf16 v[90:93], v[168:171], v[212:215], v[90:93]
	v_mfma_f32_16x16x32_bf16 v[78:81], v[160:163], v[220:223], v[78:81]
	v_mfma_f32_16x16x32_bf16 v[74:77], v[168:171], v[220:223], v[74:77]
	s_setprio 0
	s_setprio 1
	v_mfma_f32_16x16x32_bf16 v[118:121], v[176:179], v[192:195], v[118:121]
	v_mfma_f32_16x16x32_bf16 v[114:117], v[184:187], v[192:195], v[114:117]
	v_mfma_f32_16x16x32_bf16 v[102:105], v[176:179], v[200:203], v[102:105]
	v_mfma_f32_16x16x32_bf16 v[98:101], v[184:187], v[200:203], v[98:101]
	v_mfma_f32_16x16x32_bf16 v[86:89], v[176:179], v[208:211], v[86:89]
	v_mfma_f32_16x16x32_bf16 v[82:85], v[184:187], v[208:211], v[82:85]
	v_mfma_f32_16x16x32_bf16 v[70:73], v[176:179], v[216:219], v[70:73]
	v_mfma_f32_16x16x32_bf16 v[66:69], v[184:187], v[216:219], v[66:69]
	v_mfma_f32_16x16x32_bf16 v[118:121], v[180:183], v[196:199], v[118:121]
	v_mfma_f32_16x16x32_bf16 v[114:117], v[188:191], v[196:199], v[114:117]
	v_mfma_f32_16x16x32_bf16 v[102:105], v[180:183], v[204:207], v[102:105]
	v_mfma_f32_16x16x32_bf16 v[98:101], v[188:191], v[204:207], v[98:101]
	v_mfma_f32_16x16x32_bf16 v[86:89], v[180:183], v[212:215], v[86:89]
	v_mfma_f32_16x16x32_bf16 v[82:85], v[188:191], v[212:215], v[82:85]
	v_mfma_f32_16x16x32_bf16 v[70:73], v[180:183], v[220:223], v[70:73]
	v_mfma_f32_16x16x32_bf16 v[66:69], v[188:191], v[220:223], v[66:69]
	s_setprio 0
	s_barrier
	s_add_i32 s24, s62, s31
	v_lshl_add_u64 v[152:153], v[152:153], 0, s[16:17]
	s_mov_b32 m0, s24
	ds_read_b128 v[192:195], v158 offset:49152
	ds_read_b128 v[196:199], v158 offset:50176
	ds_read_b128 v[200:203], v158 offset:51200
	ds_read_b128 v[204:207], v158 offset:52224
	ds_read_b128 v[208:211], v158 offset:53248
	ds_read_b128 v[212:215], v158 offset:54272
	ds_read_b128 v[216:219], v158 offset:55296
	ds_read_b128 v[220:223], v158 offset:56320
	global_load_lds_dwordx4 v[152:153], off
	s_add_i32 m0, s24, 0x2000
	s_add_u32 s22, s22, 0x100080
	v_lshl_add_u64 v[152:153], v[172:173], 0, s[16:17]
	s_addc_u32 s23, s23, 0
	s_add_i32 s24, s63, s31
	global_load_lds_dwordx4 v[152:153], off
	v_lshl_add_u64 v[152:153], s[22:23], 0, v[136:137]
	s_mov_b32 m0, s24
	s_nop 0
	global_load_lds_dwordx4 v[152:153], off
	v_lshl_add_u64 v[152:153], s[22:23], 0, v[130:131]
	s_add_i32 m0, s24, 0x2000
	s_nop 0
	global_load_lds_dwordx4 v[152:153], off
	v_lshl_add_u64 v[152:153], v[224:225], 0, s[16:17]
	s_mov_b32 m0, s40
	s_nop 0
	global_load_lds_dwordx4 v[152:153], off
	v_lshl_add_u64 v[152:153], v[226:227], 0, s[16:17]
	s_mov_b32 m0, s41
	s_nop 0
	global_load_lds_dwordx4 v[152:153], off
	s_waitcnt vmcnt(8)
	s_waitcnt lgkmcnt(0)
	s_barrier
	s_setprio 1
	s_waitcnt lgkmcnt(0)
	v_mfma_f32_16x16x32_bf16 v[62:65], v[148:151], v[192:195], v[62:65]
	v_mfma_f32_16x16x32_bf16 v[58:61], v[164:167], v[192:195], v[58:61]
	v_mfma_f32_16x16x32_bf16 v[46:49], v[148:151], v[200:203], v[46:49]
	v_mfma_f32_16x16x32_bf16 v[42:45], v[164:167], v[200:203], v[42:45]
	v_mfma_f32_16x16x32_bf16 v[30:33], v[148:151], v[208:211], v[30:33]
	v_mfma_f32_16x16x32_bf16 v[26:29], v[164:167], v[208:211], v[26:29]
	v_mfma_f32_16x16x32_bf16 v[14:17], v[148:151], v[216:219], v[14:17]
	v_mfma_f32_16x16x32_bf16 v[10:13], v[164:167], v[216:219], v[10:13]
	v_mfma_f32_16x16x32_bf16 v[62:65], v[160:163], v[196:199], v[62:65]
	v_mfma_f32_16x16x32_bf16 v[58:61], v[168:171], v[196:199], v[58:61]
	v_mfma_f32_16x16x32_bf16 v[46:49], v[160:163], v[204:207], v[46:49]
	v_mfma_f32_16x16x32_bf16 v[42:45], v[168:171], v[204:207], v[42:45]
	v_mfma_f32_16x16x32_bf16 v[30:33], v[160:163], v[212:215], v[30:33]
	v_mfma_f32_16x16x32_bf16 v[26:29], v[168:171], v[212:215], v[26:29]
	v_mfma_f32_16x16x32_bf16 v[14:17], v[160:163], v[220:223], v[14:17]
	v_mfma_f32_16x16x32_bf16 v[10:13], v[168:171], v[220:223], v[10:13]
	s_setprio 0
	s_setprio 1
	v_mfma_f32_16x16x32_bf16 v[54:57], v[176:179], v[192:195], v[54:57]
	v_mfma_f32_16x16x32_bf16 v[50:53], v[184:187], v[192:195], v[50:53]
	v_mfma_f32_16x16x32_bf16 v[38:41], v[176:179], v[200:203], v[38:41]
	v_mfma_f32_16x16x32_bf16 v[34:37], v[184:187], v[200:203], v[34:37]
	v_mfma_f32_16x16x32_bf16 v[22:25], v[176:179], v[208:211], v[22:25]
	v_mfma_f32_16x16x32_bf16 v[18:21], v[184:187], v[208:211], v[18:21]
	v_mfma_f32_16x16x32_bf16 v[6:9], v[176:179], v[216:219], v[6:9]
	v_mfma_f32_16x16x32_bf16 v[2:5], v[184:187], v[216:219], v[2:5]
	v_mfma_f32_16x16x32_bf16 v[54:57], v[180:183], v[196:199], v[54:57]
	v_mfma_f32_16x16x32_bf16 v[50:53], v[188:191], v[196:199], v[50:53]
	v_mfma_f32_16x16x32_bf16 v[38:41], v[180:183], v[204:207], v[38:41]
	v_mfma_f32_16x16x32_bf16 v[34:37], v[188:191], v[204:207], v[34:37]
	v_mfma_f32_16x16x32_bf16 v[22:25], v[180:183], v[212:215], v[22:25]
	v_mfma_f32_16x16x32_bf16 v[18:21], v[188:191], v[212:215], v[18:21]
	v_mfma_f32_16x16x32_bf16 v[6:9], v[180:183], v[220:223], v[6:9]
	v_mfma_f32_16x16x32_bf16 v[2:5], v[188:191], v[220:223], v[2:5]
	s_setprio 0
	s_barrier
	s_add_i32 s61, s61, 2
	s_add_u32 s0, s0, 0x100
	s_addc_u32 s1, s1, 0
	s_add_u32 s59, s59, 0x100
	s_addc_u32 s60, s60, 0
	s_cmp_gt_u32 s61, 61
	s_cbranch_scc0 .LBB0_731
	v_and_b32_e32 v165, 3, v174
	v_lshrrev_b32_e32 v170, 2, v174
	v_lshlrev_b32_e32 v164, 6, v165
	v_and_or_b32 v164, v174, 60, v164
	v_and_b32_e32 v171, 15, v174
	v_sub_u32_e32 v170, v170, v171
	v_lshrrev_b32_e32 v171, 4, v174
	v_sub_u32_e32 v165, v165, v171
	v_mul_i32_i24_e32 v170, 0xac00, v170
	v_lshl_add_u32 v166, v165, 4, v170
	v_ashrrev_i32_e32 v167, 31, v166
	s_lshl_b32 s5, s56, 8
	s_add_i32 s5, s5, s39
	v_or_b32_e32 v159, s5, v1
	v_cmp_lt_i32_e64 s[0:1], s46, v159
	s_and_b64 s[22:23], s[0:1], s[18:19]
	v_mov_b64_e32 v[150:151], 0
	s_and_saveexec_b64 s[0:1], s[22:23]
	v_add_u32_e32 v148, 0xffffe000, v159
	v_lshrrev_b32_e32 v148, 2, v148
	v_and_b32_e32 v148, 0x3ffffff2, v148
	v_add_u32_e32 v150, v148, v154
	v_mov_b64_e32 v[148:149], s[10:11]
	v_mad_u64_u32 v[150:151], s[22:23], v150, s47, v[148:149]
	s_or_b64 exec, exec, s[0:1]
	v_lshl_or_b32 v148, s55, 8, v155
	v_mov_b64_e32 v[152:153], s[6:7]
	v_ashrrev_i32_e32 v149, 31, v148
	v_mad_i64_i32 v[152:153], s[0:1], v159, s48, v[152:153]
	v_lshl_add_u64 v[152:153], v[148:149], 1, v[152:153]
	v_cmp_ne_u64_e64 s[0:1], 0, v[150:151]
	v_lshl_add_u64 v[150:151], v[148:149], 2, v[150:151]
	v_cvt_pk_bf16_f32 v160, v126, v127
	v_cvt_pk_bf16_f32 v161, v128, v129
	v_cvt_pk_bf16_f32 v162, v122, v123
	v_cvt_pk_bf16_f32 v163, v124, v125
	ds_bpermute_b32 v160, v164, v160
	ds_bpermute_b32 v161, v164, v161
	ds_bpermute_b32 v162, v164, v162
	ds_bpermute_b32 v163, v164, v163
	v_lshl_add_u64 v[168:169], v[166:167], 0, v[152:153]
	s_waitcnt lgkmcnt(0)
	global_store_dwordx4 v[168:169], v[160:163], off
	s_and_saveexec_b64 s[22:23], s[0:1]
	s_cbranch_execz .LBB0_736
	global_store_dwordx4 v[150:151], v[126:129], off
	global_store_dwordx4 v[150:151], v[122:125], off offset:16
.LBB0_736:
	s_or_b64 exec, exec, s[22:23]
	s_nop 0
	v_cvt_pk_bf16_f32 v122, v118, v119
	v_cvt_pk_bf16_f32 v123, v120, v121
	v_cvt_pk_bf16_f32 v124, v114, v115
	v_cvt_pk_bf16_f32 v125, v116, v117
	ds_bpermute_b32 v122, v164, v122
	ds_bpermute_b32 v123, v164, v123
	ds_bpermute_b32 v124, v164, v124
	ds_bpermute_b32 v125, v164, v125
	v_lshl_add_u64 v[168:169], v[166:167], 0, v[152:153]
	s_waitcnt lgkmcnt(0)
	global_store_dwordx4 v[168:169], v[122:125], off offset:256
	s_and_saveexec_b64 s[22:23], s[0:1]
	s_cbranch_execz .LBB0_738
	global_store_dwordx4 v[150:151], v[118:121], off offset:512
	global_store_dwordx4 v[150:151], v[114:117], off offset:528
.LBB0_738:
	s_or_b64 exec, exec, s[22:23]
	s_nop 0
	v_or_b32_e32 v116, 16, v159
	v_cmp_lt_i32_e64 s[0:1], s46, v116
	s_and_b64 s[22:23], s[0:1], s[18:19]
	v_mov_b64_e32 v[114:115], 0
	s_and_saveexec_b64 s[0:1], s[22:23]
	v_add_u32_e32 v114, 0xffffe010, v159
	v_lshrrev_b32_e32 v114, 2, v114
	v_and_b32_e32 v114, 0x3ffffff6, v114
	v_add_u32_e32 v117, v114, v154
	v_mov_b64_e32 v[114:115], s[10:11]
	v_mad_u64_u32 v[114:115], s[22:23], v117, s47, v[114:115]
	s_or_b64 exec, exec, s[0:1]
	v_mov_b64_e32 v[118:119], s[6:7]
	v_mad_i64_i32 v[116:117], s[0:1], v116, s48, v[118:119]
	v_lshl_add_u64 v[116:117], v[148:149], 1, v[116:117]
	v_cmp_ne_u64_e64 s[0:1], 0, v[114:115]
	v_lshl_add_u64 v[114:115], v[148:149], 2, v[114:115]
	v_cvt_pk_bf16_f32 v118, v110, v111
	v_cvt_pk_bf16_f32 v119, v112, v113
	v_cvt_pk_bf16_f32 v120, v106, v107
	v_cvt_pk_bf16_f32 v121, v108, v109
	ds_bpermute_b32 v118, v164, v118
	ds_bpermute_b32 v119, v164, v119
	ds_bpermute_b32 v120, v164, v120
	ds_bpermute_b32 v121, v164, v121
	v_lshl_add_u64 v[168:169], v[166:167], 0, v[116:117]
	s_waitcnt lgkmcnt(0)
	global_store_dwordx4 v[168:169], v[118:121], off
	s_and_saveexec_b64 s[22:23], s[0:1]
	s_cbranch_execz .LBB0_742
	global_store_dwordx4 v[114:115], v[110:113], off
	global_store_dwordx4 v[114:115], v[106:109], off offset:16
.LBB0_742:
	s_or_b64 exec, exec, s[22:23]
	s_nop 0
	v_cvt_pk_bf16_f32 v106, v102, v103
	v_cvt_pk_bf16_f32 v107, v104, v105
	v_cvt_pk_bf16_f32 v108, v98, v99
	v_cvt_pk_bf16_f32 v109, v100, v101
	ds_bpermute_b32 v106, v164, v106
	ds_bpermute_b32 v107, v164, v107
	ds_bpermute_b32 v108, v164, v108
	ds_bpermute_b32 v109, v164, v109
	v_lshl_add_u64 v[168:169], v[166:167], 0, v[116:117]
	s_waitcnt lgkmcnt(0)
	global_store_dwordx4 v[168:169], v[106:109], off offset:256
	s_and_saveexec_b64 s[22:23], s[0:1]
	s_cbranch_execz .LBB0_744
	global_store_dwordx4 v[114:115], v[102:105], off offset:512
	global_store_dwordx4 v[114:115], v[98:101], off offset:528
.LBB0_744:
	s_or_b64 exec, exec, s[22:23]
	s_nop 0
	v_or_b32_e32 v100, 32, v159
	v_cmp_lt_i32_e64 s[0:1], s46, v100
	s_and_b64 s[22:23], s[0:1], s[18:19]
	v_mov_b64_e32 v[98:99], 0
	s_and_saveexec_b64 s[0:1], s[22:23]
	v_add_u32_e32 v98, 0xffffe020, v159
	v_lshrrev_b32_e32 v98, 2, v98
	v_and_b32_e32 v98, 0x3ffffffa, v98
	v_add_u32_e32 v101, v98, v154
	v_mov_b64_e32 v[98:99], s[10:11]
	v_mad_u64_u32 v[98:99], s[22:23], v101, s47, v[98:99]
	s_or_b64 exec, exec, s[0:1]
	v_mov_b64_e32 v[102:103], s[6:7]
	v_mad_i64_i32 v[100:101], s[0:1], v100, s48, v[102:103]
	v_lshl_add_u64 v[100:101], v[148:149], 1, v[100:101]
	v_cmp_ne_u64_e64 s[0:1], 0, v[98:99]
	v_lshl_add_u64 v[98:99], v[148:149], 2, v[98:99]
	v_cvt_pk_bf16_f32 v102, v94, v95
	v_cvt_pk_bf16_f32 v103, v96, v97
	v_cvt_pk_bf16_f32 v104, v90, v91
	v_cvt_pk_bf16_f32 v105, v92, v93
	ds_bpermute_b32 v102, v164, v102
	ds_bpermute_b32 v103, v164, v103
	ds_bpermute_b32 v104, v164, v104
	ds_bpermute_b32 v105, v164, v105
	v_lshl_add_u64 v[168:169], v[166:167], 0, v[100:101]
	s_waitcnt lgkmcnt(0)
	global_store_dwordx4 v[168:169], v[102:105], off
	s_and_saveexec_b64 s[22:23], s[0:1]
	s_cbranch_execz .LBB0_748
	global_store_dwordx4 v[98:99], v[94:97], off
	global_store_dwordx4 v[98:99], v[90:93], off offset:16
.LBB0_748:
	s_or_b64 exec, exec, s[22:23]
	s_nop 0
	v_cvt_pk_bf16_f32 v90, v86, v87
	v_cvt_pk_bf16_f32 v91, v88, v89
	v_cvt_pk_bf16_f32 v92, v82, v83
	v_cvt_pk_bf16_f32 v93, v84, v85
	ds_bpermute_b32 v90, v164, v90
	ds_bpermute_b32 v91, v164, v91
	ds_bpermute_b32 v92, v164, v92
	ds_bpermute_b32 v93, v164, v93
	v_lshl_add_u64 v[168:169], v[166:167], 0, v[100:101]
	s_waitcnt lgkmcnt(0)
	global_store_dwordx4 v[168:169], v[90:93], off offset:256
	s_and_saveexec_b64 s[22:23], s[0:1]
	s_cbranch_execz .LBB0_750
	global_store_dwordx4 v[98:99], v[86:89], off offset:512
	global_store_dwordx4 v[98:99], v[82:85], off offset:528

.LBB0_758:
	s_or_b64 exec, exec, s[22:23]
	v_mov_b64_e32 v[86:87], s[6:7]
	v_mad_i64_i32 v[84:85], s[0:1], v84, s48, v[86:87]
	v_lshl_add_u64 v[84:85], v[148:149], 1, v[84:85]
	v_cmp_ne_u64_e64 s[0:1], 0, v[82:83]
	v_lshl_add_u64 v[82:83], v[148:149], 2, v[82:83]
	v_cvt_pk_bf16_f32 v86, v78, v79
	v_cvt_pk_bf16_f32 v87, v80, v81
	v_cvt_pk_bf16_f32 v88, v74, v75
	v_cvt_pk_bf16_f32 v89, v76, v77
	ds_bpermute_b32 v86, v164, v86
	ds_bpermute_b32 v87, v164, v87
	ds_bpermute_b32 v88, v164, v88
	ds_bpermute_b32 v89, v164, v89
	v_lshl_add_u64 v[168:169], v[166:167], 0, v[84:85]
	s_waitcnt lgkmcnt(0)
	global_store_dwordx4 v[168:169], v[86:89], off
	s_and_saveexec_b64 s[22:23], s[0:1]
	s_cbranch_execz .LBB0_760
	global_store_dwordx4 v[82:83], v[78:81], off
	global_store_dwordx4 v[82:83], v[74:77], off offset:16
.LBB0_760:
	s_or_b64 exec, exec, s[22:23]
	s_nop 0
	v_cvt_pk_bf16_f32 v74, v70, v71
	v_cvt_pk_bf16_f32 v75, v72, v73
	v_cvt_pk_bf16_f32 v76, v66, v67
	v_cvt_pk_bf16_f32 v77, v68, v69
	ds_bpermute_b32 v74, v164, v74
	ds_bpermute_b32 v75, v164, v75
	ds_bpermute_b32 v76, v164, v76
	ds_bpermute_b32 v77, v164, v77
	v_lshl_add_u64 v[168:169], v[166:167], 0, v[84:85]
	s_waitcnt lgkmcnt(0)
	global_store_dwordx4 v[168:169], v[74:77], off offset:256
	s_and_saveexec_b64 s[22:23], s[0:1]
	s_cbranch_execz .LBB0_762
	global_store_dwordx4 v[82:83], v[70:73], off offset:512
	global_store_dwordx4 v[82:83], v[66:69], off offset:528
.LBB0_762:
	s_or_b64 exec, exec, s[22:23]
	v_cmp_lt_i32_e64 s[0:1], s51, v159
	s_and_b64 s[22:23], s[0:1], s[18:19]
	v_mov_b64_e32 v[66:67], 0
	s_and_saveexec_b64 s[0:1], s[22:23]
	v_add_u32_e32 v66, 0xffffe080, v159
	v_lshrrev_b32_e32 v66, 2, v66
	v_and_b32_e32 v66, 0x3ffffff2, v66
	v_add_u32_e32 v68, v66, v154
	v_mov_b64_e32 v[66:67], s[10:11]
	v_mad_u64_u32 v[66:67], s[22:23], v68, s47, v[66:67]
	s_or_b64 exec, exec, s[0:1]
	v_add_u32_e32 v70, 0x80, v159
	v_mov_b64_e32 v[68:69], s[6:7]
	v_mad_i64_i32 v[68:69], s[0:1], v70, s48, v[68:69]
	v_lshl_add_u64 v[68:69], v[148:149], 1, v[68:69]
	v_cmp_ne_u64_e64 s[0:1], 0, v[66:67]
	v_lshl_add_u64 v[66:67], v[148:149], 2, v[66:67]
	v_cvt_pk_bf16_f32 v72, v62, v63
	v_cvt_pk_bf16_f32 v73, v64, v65
	v_cvt_pk_bf16_f32 v74, v58, v59
	v_cvt_pk_bf16_f32 v75, v60, v61
	ds_bpermute_b32 v72, v164, v72
	ds_bpermute_b32 v73, v164, v73
	ds_bpermute_b32 v74, v164, v74
	ds_bpermute_b32 v75, v164, v75
	v_lshl_add_u64 v[168:169], v[166:167], 0, v[68:69]
	s_waitcnt lgkmcnt(0)
	global_store_dwordx4 v[168:169], v[72:75], off
	s_and_saveexec_b64 s[22:23], s[0:1]
	s_cbranch_execz .LBB0_766
	global_store_dwordx4 v[66:67], v[62:65], off
	global_store_dwordx4 v[66:67], v[58:61], off offset:16
.LBB0_766:
	s_or_b64 exec, exec, s[22:23]
	s_nop 0
	v_cvt_pk_bf16_f32 v58, v54, v55
	v_cvt_pk_bf16_f32 v59, v56, v57
	v_cvt_pk_bf16_f32 v60, v50, v51
	v_cvt_pk_bf16_f32 v61, v52, v53
	ds_bpermute_b32 v58, v164, v58
	ds_bpermute_b32 v59, v164, v59
	ds_bpermute_b32 v60, v164, v60
	ds_bpermute_b32 v61, v164, v61
	v_lshl_add_u64 v[168:169], v[166:167], 0, v[68:69]
	s_waitcnt lgkmcnt(0)
	global_store_dwordx4 v[168:169], v[58:61], off offset:256
	s_and_saveexec_b64 s[22:23], s[0:1]
	s_cbranch_execz .LBB0_768
	global_store_dwordx4 v[66:67], v[54:57], off offset:512
	global_store_dwordx4 v[66:67], v[50:53], off offset:528
.LBB0_768:
	s_or_b64 exec, exec, s[22:23]
	v_cmp_lt_i32_e64 s[0:1], s52, v159
	s_and_b64 s[22:23], s[0:1], s[18:19]
	v_mov_b64_e32 v[50:51], 0
	s_and_saveexec_b64 s[0:1], s[22:23]
	v_add_u32_e32 v50, 0xffffe090, v159
	v_lshrrev_b32_e32 v50, 2, v50
	v_and_b32_e32 v50, 0x3ffffff6, v50
	v_add_u32_e32 v52, v50, v154
	v_mov_b64_e32 v[50:51], s[10:11]
	v_mad_u64_u32 v[50:51], s[22:23], v52, s47, v[50:51]
	s_or_b64 exec, exec, s[0:1]
	v_add_u32_e32 v54, 0x90, v159
	v_mov_b64_e32 v[52:53], s[6:7]
	v_mad_i64_i32 v[52:53], s[0:1], v54, s48, v[52:53]
	v_lshl_add_u64 v[52:53], v[148:149], 1, v[52:53]
	v_cmp_ne_u64_e64 s[0:1], 0, v[50:51]
	v_lshl_add_u64 v[50:51], v[148:149], 2, v[50:51]
	v_cvt_pk_bf16_f32 v54, v46, v47
	v_cvt_pk_bf16_f32 v55, v48, v49
	v_cvt_pk_bf16_f32 v56, v42, v43
	v_cvt_pk_bf16_f32 v57, v44, v45
	ds_bpermute_b32 v54, v164, v54
	ds_bpermute_b32 v55, v164, v55
	ds_bpermute_b32 v56, v164, v56
	ds_bpermute_b32 v57, v164, v57
	v_lshl_add_u64 v[168:169], v[166:167], 0, v[52:53]
	s_waitcnt lgkmcnt(0)
	global_store_dwordx4 v[168:169], v[54:57], off
	s_and_saveexec_b64 s[22:23], s[0:1]
	s_cbranch_execz .LBB0_772
	global_store_dwordx4 v[50:51], v[46:49], off
	global_store_dwordx4 v[50:51], v[42:45], off offset:16
.LBB0_772:
	s_or_b64 exec, exec, s[22:23]
	s_nop 0
	v_cvt_pk_bf16_f32 v42, v38, v39
	v_cvt_pk_bf16_f32 v43, v40, v41
	v_cvt_pk_bf16_f32 v44, v34, v35
	v_cvt_pk_bf16_f32 v45, v36, v37
	ds_bpermute_b32 v42, v164, v42
	ds_bpermute_b32 v43, v164, v43
	ds_bpermute_b32 v44, v164, v44
	ds_bpermute_b32 v45, v164, v45
	v_lshl_add_u64 v[168:169], v[166:167], 0, v[52:53]
	s_waitcnt lgkmcnt(0)
	global_store_dwordx4 v[168:169], v[42:45], off offset:256
	s_and_saveexec_b64 s[22:23], s[0:1]
	s_cbranch_execz .LBB0_774
	global_store_dwordx4 v[50:51], v[38:41], off offset:512
	global_store_dwordx4 v[50:51], v[34:37], off offset:528
.LBB0_774:
	s_or_b64 exec, exec, s[22:23]
	v_cmp_lt_i32_e64 s[0:1], s53, v159
	s_and_b64 s[22:23], s[0:1], s[18:19]
	v_mov_b64_e32 v[34:35], 0
	s_and_saveexec_b64 s[0:1], s[22:23]
	v_add_u32_e32 v34, 0xffffe0a0, v159
	v_lshrrev_b32_e32 v34, 2, v34
	v_and_b32_e32 v34, 0x3ffffffa, v34
	v_add_u32_e32 v36, v34, v154
	v_mov_b64_e32 v[34:35], s[10:11]
	v_mad_u64_u32 v[34:35], s[22:23], v36, s47, v[34:35]
	s_or_b64 exec, exec, s[0:1]
	v_add_u32_e32 v38, 0xa0, v159
	v_mov_b64_e32 v[36:37], s[6:7]
	v_mad_i64_i32 v[36:37], s[0:1], v38, s48, v[36:37]
	v_lshl_add_u64 v[36:37], v[148:149], 1, v[36:37]
	v_cmp_ne_u64_e64 s[0:1], 0, v[34:35]
	v_lshl_add_u64 v[34:35], v[148:149], 2, v[34:35]
	v_cvt_pk_bf16_f32 v38, v30, v31
	v_cvt_pk_bf16_f32 v39, v32, v33
	v_cvt_pk_bf16_f32 v40, v26, v27
	v_cvt_pk_bf16_f32 v41, v28, v29
	ds_bpermute_b32 v38, v164, v38
	ds_bpermute_b32 v39, v164, v39
	ds_bpermute_b32 v40, v164, v40
	ds_bpermute_b32 v41, v164, v41
	v_lshl_add_u64 v[168:169], v[166:167], 0, v[36:37]
	s_waitcnt lgkmcnt(0)
	global_store_dwordx4 v[168:169], v[38:41], off
	s_and_saveexec_b64 s[22:23], s[0:1]
	s_cbranch_execz .LBB0_778
	global_store_dwordx4 v[34:35], v[30:33], off
	global_store_dwordx4 v[34:35], v[26:29], off offset:16
.LBB0_778:
	s_or_b64 exec, exec, s[22:23]
	s_nop 0
	v_cvt_pk_bf16_f32 v26, v22, v23
	v_cvt_pk_bf16_f32 v27, v24, v25
	v_cvt_pk_bf16_f32 v28, v18, v19
	v_cvt_pk_bf16_f32 v29, v20, v21
	ds_bpermute_b32 v26, v164, v26
	ds_bpermute_b32 v27, v164, v27
	ds_bpermute_b32 v28, v164, v28
	ds_bpermute_b32 v29, v164, v29
	v_lshl_add_u64 v[168:169], v[166:167], 0, v[36:37]
	s_waitcnt lgkmcnt(0)
	global_store_dwordx4 v[168:169], v[26:29], off offset:256
	s_and_saveexec_b64 s[22:23], s[0:1]
	s_cbranch_execz .LBB0_780
	global_store_dwordx4 v[34:35], v[22:25], off offset:512
	global_store_dwordx4 v[34:35], v[18:21], off offset:528

.LBB0_788:
	s_or_b64 exec, exec, s[22:23]
	v_mov_b64_e32 v[22:23], s[6:7]
	v_mad_i64_i32 v[20:21], s[0:1], v20, s48, v[22:23]
	v_lshl_add_u64 v[20:21], v[148:149], 1, v[20:21]
	v_cmp_ne_u64_e64 s[0:1], 0, v[18:19]
	v_lshl_add_u64 v[18:19], v[148:149], 2, v[18:19]
	v_cvt_pk_bf16_f32 v22, v14, v15
	v_cvt_pk_bf16_f32 v23, v16, v17
	v_cvt_pk_bf16_f32 v24, v10, v11
	v_cvt_pk_bf16_f32 v25, v12, v13
	ds_bpermute_b32 v22, v164, v22
	ds_bpermute_b32 v23, v164, v23
	ds_bpermute_b32 v24, v164, v24
	ds_bpermute_b32 v25, v164, v25
	v_lshl_add_u64 v[168:169], v[166:167], 0, v[20:21]
	s_waitcnt lgkmcnt(0)
	global_store_dwordx4 v[168:169], v[22:25], off
	s_and_saveexec_b64 s[22:23], s[0:1]
	s_cbranch_execz .LBB0_790
	global_store_dwordx4 v[18:19], v[14:17], off
	global_store_dwordx4 v[18:19], v[10:13], off offset:16
.LBB0_790:
	s_or_b64 exec, exec, s[22:23]
	s_nop 0
	v_cvt_pk_bf16_f32 v10, v6, v7
	v_cvt_pk_bf16_f32 v11, v8, v9
	v_cvt_pk_bf16_f32 v12, v2, v3
	v_cvt_pk_bf16_f32 v13, v4, v5
	ds_bpermute_b32 v10, v164, v10
	ds_bpermute_b32 v11, v164, v11
	ds_bpermute_b32 v12, v164, v12
	ds_bpermute_b32 v13, v164, v13
	v_lshl_add_u64 v[168:169], v[166:167], 0, v[20:21]
	s_waitcnt lgkmcnt(0)
	global_store_dwordx4 v[168:169], v[10:13], off offset:256
	s_and_saveexec_b64 s[22:23], s[0:1]
	s_cbranch_execz .LBB0_729
	global_store_dwordx4 v[18:19], v[6:9], off offset:512
	global_store_dwordx4 v[18:19], v[2:5], off offset:528
	s_branch .LBB0_729
